# P0 setup phase: transposes per workgroup re-split by class (3 / 6 / ~8.7) after the filter items got cheaper
# baseline (speedup 1.0000x reference)
.Lp0_c3t:
	s_cmpk_lt_u32 s99, 0xc0
	s_cbranch_scc0 .Lp0_cB
	s_cmp_lt_u32 s98, 6
	s_cbranch_scc0 .LBB0_21
	s_mul_i32 s25, s99, 3
	s_add_i32 s25, s25, s98
	s_addk_i32 s25, 0x53e
	s_branch .LBB0_392
.Lp0_cB:
	s_cmp_lt_u32 s98, 9
	s_cbranch_scc0 .LBB0_21
	s_mul_i32 s25, s99, 6
	s_add_i32 s25, s25, s98
	s_addk_i32 s25, 0x2fe
	s_branch .LBB0_392
.Lp0_c2:
	s_cmp_lt_u32 s98, 11
	s_cbranch_scc0 .LBB0_21
	s_add_i32 s25, s98, -2
	s_mulk_i32 s25, 0xc0
	s_add_i32 s25, s25, s99
	s_addk_i32 s25, 0x400
	s_cmpk_lt_u32 s25, 0xbc0
	s_cbranch_scc0 .Lp0_misc
	s_addk_i32 s25, 0x541
	s_branch .LBB0_392
